# k20 + nt hint on the read-once row loads of the three row-norm phases (hrows1, hrows2, final)
# baseline (speedup 1.0000x reference)
; __device__ void phase_hrows(const Params& p, const float* srcp, const float* srcs, const float* gamma, int sh_off, int sc_off, bf16_t* h, int wave) {
;     ...
;     for (int g0 = blockIdx.x * 8 + wv; g0 < NTOK; g0 += 2 * stride) {
;         f32x4 v[2][4]; float ss[2];
; #pragma unroll
;         for (int u = 0; u < 2; ++u) { const int g = g0 + u * stride; ss[u] = 0.f;
;             if (g < NTOK) { const float* x = g < NPTOK ? srcp + (size_t)g * D : srcs + (size_t)(g - NPTOK) * D;
; #pragma unroll
;                 for (int i = 0; i < 4; ++i) v[u][i] = *(const f32x4*)(x + lane * 8 + 512 * (i >> 1) + 4 * (i & 1)); } }
.LBB0_152:
	v_add_u32_e32 v18, 0xffff0000, v59
	v_lshl_add_u64 v[16:17], v[32:33], 0, s[20:21]
	v_cmp_gt_i32_e32 vcc, s23, v59
	v_add_u32_e32 v60, s22, v59
	s_nop 0
	v_cndmask_b32_e32 v17, 0, v17, vcc
	v_cndmask_b32_e32 v16, v18, v16, vcc
	v_cndmask_b32_e32 v19, v54, v55, vcc
	v_cndmask_b32_e32 v18, v56, v57, vcc
	v_lshlrev_b64 v[16:17], 12, v[16:17]
	v_lshl_add_u64 v[16:17], v[18:19], 0, v[16:17]
	v_lshl_add_u64 v[20:21], v[16:17], 0, v[34:35]
	global_load_dwordx4 v[24:27], v[20:21], off offset:16 nt
	global_load_dwordx4 v[28:31], v[20:21], off nt
	global_load_dwordx4 v[16:19], v[20:21], off offset:2064 nt
	s_nop 0
	global_load_dwordx4 v[20:23], v[20:21], off offset:2048 nt
	v_cmp_gt_i32_e32 vcc, s3, v60
	s_and_saveexec_b64 s[4:5], vcc
	s_cbranch_execz .LBB0_154
	v_readlane_b32 s36, v253, 12
	v_lshl_add_u64 v[0:1], v[40:41], 0, s[20:21]
	v_add_u32_e32 v2, 0xffff0000, v60
	v_cmp_gt_i32_e64 s[0:1], s23, v60
	v_readlane_b32 s37, v253, 13
	v_readlane_b32 s39, v253, 15
	v_cndmask_b32_e64 v0, v2, v0, s[0:1]
	v_readlane_b32 s38, v253, 14
	v_mov_b32_e32 v2, s39
	v_mov_b32_e32 v3, s37
	v_cndmask_b32_e64 v1, 0, v1, s[0:1]
	v_cndmask_b32_e64 v3, v2, v3, s[0:1]
	v_mov_b32_e32 v2, s38
	v_mov_b32_e32 v4, s36
	v_cndmask_b32_e64 v2, v2, v4, s[0:1]
	v_lshlrev_b64 v[0:1], 12, v[0:1]
	v_lshl_add_u64 v[0:1], v[2:3], 0, v[0:1]
	v_lshl_add_u64 v[12:13], v[0:1], 0, v[34:35]
	global_load_dwordx4 v[0:3], v[12:13], off offset:16 nt
	global_load_dwordx4 v[4:7], v[12:13], off nt
	global_load_dwordx4 v[8:11], v[12:13], off offset:2064 nt
	s_nop 0
	global_load_dwordx4 v[12:15], v[12:13], off offset:2048 nt
	v_readlane_b32 s40, v253, 16
	v_readlane_b32 s41, v253, 17
	v_readlane_b32 s42, v253, 18
	v_readlane_b32 s43, v253, 19
	v_readlane_b32 s44, v253, 20
	v_readlane_b32 s45, v253, 21
	v_readlane_b32 s46, v253, 22
	v_readlane_b32 s47, v253, 23
	v_readlane_b32 s48, v253, 24
	v_readlane_b32 s49, v253, 25
	v_readlane_b32 s50, v253, 26
	v_readlane_b32 s51, v253, 27

; __device__ void phase_hrows(const Params& p, const float* srcp, const float* srcs, const float* gamma, int sh_off, int sc_off, bf16_t* h, int wave) {
;     ...
;     for (int g0 = blockIdx.x * 8 + wv; g0 < NTOK; g0 += 2 * stride) {
;         f32x4 v[2][4]; float ss[2];
; #pragma unroll
;         for (int u = 0; u < 2; ++u) { const int g = g0 + u * stride; ss[u] = 0.f;
;             if (g < NTOK) { const float* x = g < NPTOK ? srcp + (size_t)g * D : srcs + (size_t)(g - NPTOK) * D;
; #pragma unroll
;                 for (int i = 0; i < 4; ++i) v[u][i] = *(const f32x4*)(x + lane * 8 + 512 * (i >> 1) + 4 * (i & 1)); } }
.LBB0_786:
	v_add_u32_e32 v16, 0xffff0000, v42
	v_ashrrev_i32_e32 v43, 31, v42
	v_cmp_gt_i32_e32 vcc, s21, v42
	s_nop 1
	v_cndmask_b32_e32 v17, 0, v43, vcc
	v_cndmask_b32_e32 v16, v16, v42, vcc
	v_cndmask_b32_e32 v19, v50, v51, vcc
	v_cndmask_b32_e32 v18, v52, v53, vcc
	v_lshlrev_b64 v[16:17], 12, v[16:17]
	v_lshl_add_u64 v[16:17], v[18:19], 0, v[16:17]
	v_lshl_add_u64 v[40:41], v[16:17], 0, v[32:33]
	global_load_dwordx4 v[24:27], v[40:41], off offset:16 nt
	global_load_dwordx4 v[28:31], v[40:41], off nt
	global_load_dwordx4 v[16:19], v[40:41], off offset:2064 nt
	global_load_dwordx4 v[20:23], v[40:41], off offset:2048 nt
	v_add_u32_e32 v40, s20, v42
	v_cmp_gt_i32_e32 vcc, s3, v40
	s_and_saveexec_b64 s[16:17], vcc
	s_cbranch_execz .LBB0_788
	v_readlane_b32 s24, v253, 8
	v_ashrrev_i32_e32 v0, 31, v40
	v_add_u32_e32 v2, 0xffff0000, v40
	v_cmp_gt_i32_e64 s[0:1], s21, v40
	v_readlane_b32 s25, v253, 9
	v_mov_b32_e32 v4, s24
	v_cndmask_b32_e64 v1, 0, v0, s[0:1]
	v_cndmask_b32_e64 v0, v2, v40, s[0:1]
	v_mov_b32_e32 v2, s19
	v_mov_b32_e32 v3, s25
	v_cndmask_b32_e64 v3, v2, v3, s[0:1]
	v_mov_b32_e32 v2, s18
	v_cndmask_b32_e64 v2, v2, v4, s[0:1]
	v_lshlrev_b64 v[0:1], 12, v[0:1]
	v_lshl_add_u64 v[0:1], v[2:3], 0, v[0:1]
	v_lshl_add_u64 v[56:57], v[0:1], 0, v[32:33]
	global_load_dwordx4 v[0:3], v[56:57], off offset:16 nt
	global_load_dwordx4 v[4:7], v[56:57], off nt
	global_load_dwordx4 v[8:11], v[56:57], off offset:2064 nt
	global_load_dwordx4 v[12:15], v[56:57], off offset:2048 nt
	v_readlane_b32 s26, v253, 10
	v_readlane_b32 s27, v253, 11

; __device__ void phase_final(const Params& p, int wave) {
;     ...
;     for (int g0 = blockIdx.x * 8 + wv; g0 < NTOK; g0 += 2 * stride) {
;         f32x4 v[2][4]; float ss[2];
; #pragma unroll
;         for (int u = 0; u < 2; ++u) { const int g = g0 + u * stride; ss[u] = 0.f;
;             if (g < NTOK) { const float* x = p.out + (size_t)g * D;
; #pragma unroll
;                 for (int i = 0; i < 4; ++i) v[u][i] = *(const f32x4*)(x + lane * 8 + 512 * (i >> 1) + 4 * (i & 1)); } }
.LBB0_908:
	v_ashrrev_i32_e32 v37, 31, v36
	v_lshlrev_b64 v[16:17], 12, v[36:37]
	v_lshl_add_u64 v[38:39], v[32:33], 0, v[16:17]
	global_load_dwordx4 v[24:27], v[38:39], off offset:16 nt
	global_load_dwordx4 v[28:31], v[38:39], off nt
	global_load_dwordx4 v[16:19], v[38:39], off offset:2064 nt
	global_load_dwordx4 v[20:23], v[38:39], off offset:2048 nt
	v_add_u32_e32 v36, s5, v36
	v_cmp_gt_i32_e32 vcc, s4, v36
	s_and_saveexec_b64 s[0:1], vcc
	s_cbranch_execz .LBB0_910
	v_ashrrev_i32_e32 v37, 31, v36
	v_lshlrev_b64 v[0:1], 12, v[36:37]
	v_lshl_add_u64 v[48:49], v[32:33], 0, v[0:1]
	global_load_dwordx4 v[0:3], v[48:49], off offset:16 nt
	global_load_dwordx4 v[4:7], v[48:49], off nt
	global_load_dwordx4 v[8:11], v[48:49], off offset:2064 nt
	global_load_dwordx4 v[12:15], v[48:49], off offset:2048 nt
